# grid barrier: first-arriving workgroup of each XCD issues an early L2 write-back while it waits (on v48)
# baseline (speedup 1.0000x reference)
; __device__ __forceinline__ unsigned xb_ld(unsigned* p)              { return __hip_atomic_load(p, __ATOMIC_RELAXED, __HIP_MEMORY_SCOPE_AGENT); }
; __device__ __forceinline__ unsigned xb_add(unsigned* p, unsigned v) { return __hip_atomic_fetch_add(p, v, __ATOMIC_RELAXED, __HIP_MEMORY_SCOPE_AGENT); }
; #define XB_SPIN(cond, bar) do { unsigned _sp = 0; while (cond) { __builtin_amdgcn_s_sleep(1); \
;     if ((++_sp & 255u) == 0u) { if (xb_ld(&(bar)[XB_TMO])) break; if (_sp > XB_SPIN_CAP) { atomicAdd(&(bar)[XB_TMO], 1u); break; } } } } while (0)
; __device__ __forceinline__ void xcd_barrier(unsigned* bar, volatile LAS unsigned* st, const int wid0) {
;     ...
;         const unsigned old = xb_add(&bar[XB_XSUB(x)], 1u);
;         const unsigned gen = old / nloc;
;         if (old + 1u == (gen + 1u) * nloc) {
;             __builtin_amdgcn_fence(__ATOMIC_RELEASE, "agent");
;             asm volatile("s_waitcnt vmcnt(0)" ::: "memory");
;             const unsigned og = xb_add(&bar[XB_TOP], 1u);
;             const unsigned tg = og / nx;
;             if (og + 1u == (tg + 1u) * nx) xb_add(&bar[XB_TOPGEN], 1u);
;             else XB_SPIN(xb_ld(&bar[XB_TOPGEN]) == tg, bar);
;             __builtin_amdgcn_fence(__ATOMIC_ACQUIRE, "agent");
;             xb_add(&bar[XB_XGEN(x)], 1u);
;             asm volatile("s_waitcnt vmcnt(0)" ::: "memory");
;         } else {
;             XB_SPIN(xb_ld(&bar[XB_XGEN(x)]) == gen, bar);
.LBB0_438:
	s_or_b64 exec, exec, s[8:9]
	v_cvt_f32_u32_e32 v4, v2
	s_waitcnt vmcnt(0)
	v_readfirstlane_b32 s3, v3
	v_sub_u32_e32 v3, 0, v2
	v_rcp_iflag_f32_e32 v4, v4
	v_add_u32_e32 v5, s3, v1
	v_mul_f32_e32 v4, 0x4f7ffffe, v4
	v_cvt_u32_f32_e32 v4, v4
	v_mul_lo_u32 v1, v3, v4
	v_mul_hi_u32 v1, v4, v1
	v_add_u32_e32 v1, v4, v1
	v_mul_hi_u32 v1, v5, v1
	v_mul_lo_u32 v3, v1, v2
	v_sub_u32_e32 v3, v5, v3
	v_add_u32_e32 v4, 1, v1
	v_cmp_ge_u32_e32 vcc, v3, v2
	s_nop 1
	v_cndmask_b32_e32 v1, v1, v4, vcc
	v_sub_u32_e32 v4, v3, v2
	v_cndmask_b32_e32 v3, v3, v4, vcc
	v_add_u32_e32 v4, 1, v1
	v_cmp_ge_u32_e32 vcc, v3, v2
	v_add_u32_e32 v3, 1, v5
	s_nop 0
	v_cndmask_b32_e32 v1, v1, v4, vcc
	v_mul_lo_u32 v4, v2, v1
	v_add_u32_e32 v2, v4, v2
	v_cmp_ne_u32_e32 vcc, v3, v2
	s_and_saveexec_b64 s[6:7], vcc
	s_xor_b64 s[6:7], exec, s[6:7]
	s_cbranch_execz .LBB0_452
	s_waitcnt lgkmcnt(0)
	v_mov_b32_e32 v0, 0x2000
	v_cmp_eq_u32_e32 vcc, v5, v4
	s_cbranch_vccz .Lwbf_0
	buffer_wbl2 sc1
.Lwbf_0:
	s_add_u32 s12, s26, 0x7181100
	s_addc_u32 s13, s27, 0
	global_load_dword v0, v0, s[12:13] offset:1024 sc1
	s_add_u32 s12, s12, 0x2400
	s_addc_u32 s13, s13, 0
	s_waitcnt vmcnt(0)
	v_cmp_eq_u32_e32 vcc, v0, v1
	s_and_saveexec_b64 s[8:9], vcc
	s_cbranch_execz .LBB0_451
	s_add_u32 s10, s26, 0x7180200
	s_addc_u32 s11, s27, 0
	s_mov_b32 s3, 1
	s_mov_b64 s[14:15], 0
	v_mov_b32_e32 v0, 0
	s_branch .LBB0_442

; __device__ __forceinline__ unsigned xb_ld(unsigned* p)              { return __hip_atomic_load(p, __ATOMIC_RELAXED, __HIP_MEMORY_SCOPE_AGENT); }
; __device__ __forceinline__ unsigned xb_add(unsigned* p, unsigned v) { return __hip_atomic_fetch_add(p, v, __ATOMIC_RELAXED, __HIP_MEMORY_SCOPE_AGENT); }
; #define XB_SPIN(cond, bar) do { unsigned _sp = 0; while (cond) { __builtin_amdgcn_s_sleep(1); \
;     if ((++_sp & 255u) == 0u) { if (xb_ld(&(bar)[XB_TMO])) break; if (_sp > XB_SPIN_CAP) { atomicAdd(&(bar)[XB_TMO], 1u); break; } } } } while (0)
; __device__ __forceinline__ void xcd_barrier(unsigned* bar, volatile LAS unsigned* st, const int wid0) {
;     ...
;         const unsigned old = xb_add(&bar[XB_XSUB(x)], 1u);
;         const unsigned gen = old / nloc;
;         if (old + 1u == (gen + 1u) * nloc) {
;             __builtin_amdgcn_fence(__ATOMIC_RELEASE, "agent");
;             asm volatile("s_waitcnt vmcnt(0)" ::: "memory");
;             const unsigned og = xb_add(&bar[XB_TOP], 1u);
;             const unsigned tg = og / nx;
;             if (og + 1u == (tg + 1u) * nx) xb_add(&bar[XB_TOPGEN], 1u);
;             else XB_SPIN(xb_ld(&bar[XB_TOPGEN]) == tg, bar);
;             __builtin_amdgcn_fence(__ATOMIC_ACQUIRE, "agent");
;             xb_add(&bar[XB_XGEN(x)], 1u);
;             asm volatile("s_waitcnt vmcnt(0)" ::: "memory");
;         } else {
;             XB_SPIN(xb_ld(&bar[XB_XGEN(x)]) == gen, bar);
.LBB0_847:
	s_or_b64 exec, exec, s[12:13]
	v_cvt_f32_u32_e32 v4, v2
	s_waitcnt vmcnt(0)
	v_readfirstlane_b32 s2, v3
	v_sub_u32_e32 v3, 0, v2
	v_rcp_iflag_f32_e32 v4, v4
	v_add_u32_e32 v5, s2, v1
	v_mul_f32_e32 v4, 0x4f7ffffe, v4
	v_cvt_u32_f32_e32 v4, v4
	v_mul_lo_u32 v1, v3, v4
	v_mul_hi_u32 v1, v4, v1
	v_add_u32_e32 v1, v4, v1
	v_mul_hi_u32 v1, v5, v1
	v_mul_lo_u32 v3, v1, v2
	v_sub_u32_e32 v3, v5, v3
	v_add_u32_e32 v4, 1, v1
	v_cmp_ge_u32_e32 vcc, v3, v2
	s_nop 1
	v_cndmask_b32_e32 v1, v1, v4, vcc
	v_sub_u32_e32 v4, v3, v2
	v_cndmask_b32_e32 v3, v3, v4, vcc
	v_add_u32_e32 v4, 1, v1
	v_cmp_ge_u32_e32 vcc, v3, v2
	v_add_u32_e32 v3, 1, v5
	s_nop 0
	v_cndmask_b32_e32 v1, v1, v4, vcc
	v_mul_lo_u32 v4, v2, v1
	v_add_u32_e32 v2, v4, v2
	v_cmp_ne_u32_e32 vcc, v3, v2
	s_and_saveexec_b64 s[2:3], vcc
	s_xor_b64 s[8:9], exec, s[2:3]
	s_cbranch_execz .LBB0_861
	s_waitcnt lgkmcnt(0)
	v_mov_b32_e32 v0, 0x2000
	v_cmp_eq_u32_e32 vcc, v5, v4
	s_cbranch_vccz .Lwbf_1
	buffer_wbl2 sc1
.Lwbf_1:
	s_add_u32 s30, s26, 0x7181100
	s_addc_u32 s31, s27, 0
	global_load_dword v0, v0, s[30:31] offset:1024 sc1
	s_add_u32 s30, s30, 0x2400
	s_addc_u32 s31, s31, 0
	s_waitcnt vmcnt(0)
	v_cmp_eq_u32_e32 vcc, v0, v1
	s_and_saveexec_b64 s[12:13], vcc
	s_cbranch_execz .LBB0_860
	s_mov_b32 s2, 1
	s_mov_b64 s[34:35], 0
	s_branch .LBB0_851

; __device__ __forceinline__ unsigned xb_ld(unsigned* p)              { return __hip_atomic_load(p, __ATOMIC_RELAXED, __HIP_MEMORY_SCOPE_AGENT); }
; __device__ __forceinline__ unsigned xb_add(unsigned* p, unsigned v) { return __hip_atomic_fetch_add(p, v, __ATOMIC_RELAXED, __HIP_MEMORY_SCOPE_AGENT); }
; #define XB_SPIN(cond, bar) do { unsigned _sp = 0; while (cond) { __builtin_amdgcn_s_sleep(1); \
;     if ((++_sp & 255u) == 0u) { if (xb_ld(&(bar)[XB_TMO])) break; if (_sp > XB_SPIN_CAP) { atomicAdd(&(bar)[XB_TMO], 1u); break; } } } } while (0)
; __device__ __forceinline__ void xcd_barrier(unsigned* bar, volatile LAS unsigned* st, const int wid0) {
;     ...
;         const unsigned old = xb_add(&bar[XB_XSUB(x)], 1u);
;         const unsigned gen = old / nloc;
;         if (old + 1u == (gen + 1u) * nloc) {
;             __builtin_amdgcn_fence(__ATOMIC_RELEASE, "agent");
;             asm volatile("s_waitcnt vmcnt(0)" ::: "memory");
;             const unsigned og = xb_add(&bar[XB_TOP], 1u);
;             const unsigned tg = og / nx;
;             if (og + 1u == (tg + 1u) * nx) xb_add(&bar[XB_TOPGEN], 1u);
;             else XB_SPIN(xb_ld(&bar[XB_TOPGEN]) == tg, bar);
;             __builtin_amdgcn_fence(__ATOMIC_ACQUIRE, "agent");
;             xb_add(&bar[XB_XGEN(x)], 1u);
;             asm volatile("s_waitcnt vmcnt(0)" ::: "memory");
;         } else {
;             XB_SPIN(xb_ld(&bar[XB_XGEN(x)]) == gen, bar);
.LBB0_997:
	s_or_b64 exec, exec, s[10:11]
	v_cvt_f32_u32_e32 v4, v2
	s_waitcnt vmcnt(0)
	v_readfirstlane_b32 s2, v3
	v_sub_u32_e32 v3, 0, v2
	v_rcp_iflag_f32_e32 v4, v4
	v_add_u32_e32 v5, s2, v1
	v_mul_f32_e32 v4, 0x4f7ffffe, v4
	v_cvt_u32_f32_e32 v4, v4
	v_mul_lo_u32 v1, v3, v4
	v_mul_hi_u32 v1, v4, v1
	v_add_u32_e32 v1, v4, v1
	v_mul_hi_u32 v1, v5, v1
	v_mul_lo_u32 v3, v1, v2
	v_sub_u32_e32 v3, v5, v3
	v_add_u32_e32 v4, 1, v1
	v_cmp_ge_u32_e32 vcc, v3, v2
	s_nop 1
	v_cndmask_b32_e32 v1, v1, v4, vcc
	v_sub_u32_e32 v4, v3, v2
	v_cndmask_b32_e32 v3, v3, v4, vcc
	v_add_u32_e32 v4, 1, v1
	v_cmp_ge_u32_e32 vcc, v3, v2
	v_add_u32_e32 v3, 1, v5
	s_nop 0
	v_cndmask_b32_e32 v1, v1, v4, vcc
	v_mul_lo_u32 v4, v2, v1
	v_add_u32_e32 v2, v4, v2
	v_cmp_ne_u32_e32 vcc, v3, v2
	s_and_saveexec_b64 s[2:3], vcc
	s_xor_b64 s[8:9], exec, s[2:3]
	s_cbranch_execz .LBB0_1011
	s_waitcnt lgkmcnt(0)
	v_mov_b32_e32 v0, 0x2000
	v_cmp_eq_u32_e32 vcc, v5, v4
	s_cbranch_vccz .Lwbf_2
	buffer_wbl2 sc1
.Lwbf_2:
	s_add_u32 s30, s26, 0x7181100
	s_addc_u32 s31, s27, 0
	global_load_dword v0, v0, s[30:31] offset:1024 sc1
	s_add_u32 s30, s30, 0x2400
	s_addc_u32 s31, s31, 0
	s_waitcnt vmcnt(0)
	v_cmp_eq_u32_e32 vcc, v0, v1
	s_and_saveexec_b64 s[10:11], vcc
	s_cbranch_execz .LBB0_1010
	s_mov_b32 s2, 1
	s_mov_b64 s[34:35], 0
	s_branch .LBB0_1001

; __device__ __forceinline__ unsigned xb_ld(unsigned* p)              { return __hip_atomic_load(p, __ATOMIC_RELAXED, __HIP_MEMORY_SCOPE_AGENT); }
; __device__ __forceinline__ unsigned xb_add(unsigned* p, unsigned v) { return __hip_atomic_fetch_add(p, v, __ATOMIC_RELAXED, __HIP_MEMORY_SCOPE_AGENT); }
; #define XB_SPIN(cond, bar) do { unsigned _sp = 0; while (cond) { __builtin_amdgcn_s_sleep(1); \
;     if ((++_sp & 255u) == 0u) { if (xb_ld(&(bar)[XB_TMO])) break; if (_sp > XB_SPIN_CAP) { atomicAdd(&(bar)[XB_TMO], 1u); break; } } } } while (0)
; __device__ __forceinline__ void xcd_barrier(unsigned* bar, volatile LAS unsigned* st, const int wid0) {
;     ...
;         const unsigned old = xb_add(&bar[XB_XSUB(x)], 1u);
;         const unsigned gen = old / nloc;
;         if (old + 1u == (gen + 1u) * nloc) {
;             __builtin_amdgcn_fence(__ATOMIC_RELEASE, "agent");
;             asm volatile("s_waitcnt vmcnt(0)" ::: "memory");
;             const unsigned og = xb_add(&bar[XB_TOP], 1u);
;             const unsigned tg = og / nx;
;             if (og + 1u == (tg + 1u) * nx) xb_add(&bar[XB_TOPGEN], 1u);
;             else XB_SPIN(xb_ld(&bar[XB_TOPGEN]) == tg, bar);
;             __builtin_amdgcn_fence(__ATOMIC_ACQUIRE, "agent");
;             xb_add(&bar[XB_XGEN(x)], 1u);
;             asm volatile("s_waitcnt vmcnt(0)" ::: "memory");
;         } else {
;             XB_SPIN(xb_ld(&bar[XB_XGEN(x)]) == gen, bar);
.LBB0_1096:
	s_or_b64 exec, exec, s[30:31]
	v_cvt_f32_u32_e32 v4, v2
	s_waitcnt vmcnt(0)
	v_readfirstlane_b32 s2, v3
	v_sub_u32_e32 v3, 0, v2
	v_rcp_iflag_f32_e32 v4, v4
	v_add_u32_e32 v5, s2, v1
	v_mul_f32_e32 v4, 0x4f7ffffe, v4
	v_cvt_u32_f32_e32 v4, v4
	v_mul_lo_u32 v1, v3, v4
	v_mul_hi_u32 v1, v4, v1
	v_add_u32_e32 v1, v4, v1
	v_mul_hi_u32 v1, v5, v1
	v_mul_lo_u32 v3, v1, v2
	v_sub_u32_e32 v3, v5, v3
	v_add_u32_e32 v4, 1, v1
	v_cmp_ge_u32_e32 vcc, v3, v2
	s_nop 1
	v_cndmask_b32_e32 v1, v1, v4, vcc
	v_sub_u32_e32 v4, v3, v2
	v_cndmask_b32_e32 v3, v3, v4, vcc
	v_add_u32_e32 v4, 1, v1
	v_cmp_ge_u32_e32 vcc, v3, v2
	v_add_u32_e32 v3, 1, v5
	s_nop 0
	v_cndmask_b32_e32 v1, v1, v4, vcc
	v_mul_lo_u32 v4, v2, v1
	v_add_u32_e32 v2, v4, v2
	v_cmp_ne_u32_e32 vcc, v3, v2
	s_and_saveexec_b64 s[2:3], vcc
	s_xor_b64 s[10:11], exec, s[2:3]
	s_cbranch_execz .LBB0_1110
	s_waitcnt lgkmcnt(0)
	v_mov_b32_e32 v0, 0x2000
	v_cmp_eq_u32_e32 vcc, v5, v4
	s_cbranch_vccz .Lwbf_3
	buffer_wbl2 sc1
.Lwbf_3:
	s_add_u32 s34, s26, 0x7181100
	s_addc_u32 s35, s27, 0
	global_load_dword v0, v0, s[34:35] offset:1024 sc1
	s_add_u32 s34, s34, 0x2400
	s_addc_u32 s35, s35, 0
	s_waitcnt vmcnt(0)
	v_cmp_eq_u32_e32 vcc, v0, v1
	s_and_saveexec_b64 s[30:31], vcc
	s_cbranch_execz .LBB0_1109
	s_mov_b32 s2, 1
	s_mov_b64 s[36:37], 0
	s_branch .LBB0_1100
